# v36 + slot position shared by the four workgroups that read one head's K/V: slot_at = ((idx>>2) + xcd) % 5
# speedup vs baseline: 1.0019x; 1.0019x over previous
.Lattn_prio_skip:
	s_add_u32 s66, s74, 0x1c600000
	s_addc_u32 s67, s75, 0
	s_add_u32 s76, s74, 0x1e600000
	s_addc_u32 s77, s75, 0
	s_add_u32 s80, s74, 0x20600000
	s_addc_u32 s81, s75, 0
	s_add_u32 s82, s74, 0x26600000
	s_addc_u32 s83, s75, 0
	s_add_u32 s84, s74, 0x2a600000
	s_addc_u32 s85, s75, 0
	s_add_u32 s6, s74, 0x180000
	s_addc_u32 s7, s75, 0
	s_ashr_i32 s0, s14, 3
	s_lshr_b32 s0, s0, 2
	s_and_b32 s1, s14, 7
	s_add_i32 s0, s0, s1
	s_mul_hi_i32 s1, s0, 0x66666667
	s_lshr_b32 s2, s1, 31
	s_ashr_i32 s1, s1, 1
	v_writelane_b32 v255, s94, 20
	s_add_i32 s1, s1, s2
	s_mul_i32 s1, s1, 5
	v_writelane_b32 v255, s95, 21
	v_writelane_b32 v255, s88, 18
	s_sub_i32 s86, s0, s1
	s_cmpk_lt_i32 s78, 0x100
	v_writelane_b32 v255, s89, 19
	v_writelane_b32 v255, s97, 22
	s_cselect_b64 s[0:1], -1, 0
	v_writelane_b32 v255, s0, 23
	s_cmpk_gt_i32 s78, 0xff
	s_nop 0
	v_writelane_b32 v255, s1, 24
	s_cbranch_scc1 .LBB0_402
	s_cmp_gt_i32 s86, 0
	s_cselect_b64 s[0:1], -1, 0
	s_add_u32 s16, s74, 0x180010
	v_cndmask_b32_e64 v1, 0, 1, s[0:1]
	s_waitcnt vmcnt(0) lgkmcnt(0)
	v_mbcnt_lo_u32_b32 v2, -1, 0
	s_mov_b32 s11, 0
	s_addc_u32 s17, s75, 0
	v_cmp_ne_u32_e64 s[2:3], 1, v1
	v_mov_b32_e32 v3, 0
	s_mov_b64 s[18:19], 0x80
	s_mov_b64 s[20:21], 0x40000
	s_mov_b64 s[22:23], 0x80000
	s_mov_b64 s[24:25], 0xc0000
	s_mov_b64 s[26:27], 0x100000
	s_mov_b32 s87, 0x41000000
	v_mov_b32_e32 v1, 0x358637bd
	s_mov_b32 s88, 0xf800000
	v_mov_b32_e32 v223, 0x260
	s_mov_b32 s89, 0x3f4ccccd
	v_mov_b32_e32 v230, 0xff800000
	v_mbcnt_hi_u32_b32 v231, -1, v2
	s_mov_b32 s90, s78
	s_branch .LBB0_297
